# gu GEMM K-loop: LDS-DMA issue moved ahead of the fragment ds_reads in each load segment
# baseline (speedup 1.0000x reference)
.LBB0_169:
	s_add_u32 s26, s34, 0xfffc0080
	s_addc_u32 s27, s35, -1
	s_add_i32 s73, 0, 0x10000
	s_cmp_eq_u32 s72, 12
	s_cselect_b32 s97, s2, s27
	s_cselect_b32 s96, s13, s26
	s_cselect_b32 s27, s11, s65
	s_cselect_b32 s26, s25, s63
	s_add_i32 s76, 0, 0x14000
	v_lshl_add_u64 v[240:241], s[34:35], 0, v[138:139]
	s_add_i32 m0, s31, 0xc000
	s_nop 0
	global_load_lds_dwordx4 v[240:241], off
	v_lshl_add_u64 v[242:243], s[34:35], 0, v[140:141]
	s_add_i32 m0, s31, 0xe000
	s_nop 0
	global_load_lds_dwordx4 v[242:243], off
	v_add_u32_e32 v144, s73, v146
	ds_read_b128 v[150:153], v144
	ds_read_b128 v[154:157], v144 offset:1024
	ds_read_b128 v[158:161], v144 offset:2048
	ds_read_b128 v[162:165], v144 offset:3072
	v_add_u32_e32 v144, s76, v146
	ds_read_b128 v[166:169], v144
	ds_read_b128 v[170:173], v144 offset:1024
	ds_read_b128 v[174:177], v144 offset:2048
	ds_read_b128 v[178:181], v144 offset:3072
	ds_read_b128 v[182:185], v148
	ds_read_b128 v[192:195], v148 offset:1024
	ds_read_b128 v[196:199], v148 offset:2048
	ds_read_b128 v[200:203], v148 offset:3072
	ds_read_b128 v[204:207], v148 offset:4096
	ds_read_b128 v[208:211], v148 offset:5120
	ds_read_b128 v[212:215], v148 offset:6144
	ds_read_b128 v[216:219], v148 offset:7168
	s_waitcnt vmcnt(8)
	s_waitcnt lgkmcnt(0)
	s_barrier
	s_setprio 1
	s_waitcnt lgkmcnt(0)
	v_mfma_f32_16x16x32_bf16 v[126:129], v[150:153], v[182:185], v[126:129]
	v_mfma_f32_16x16x32_bf16 v[118:121], v[158:161], v[182:185], v[118:121]
	v_mfma_f32_16x16x32_bf16 v[110:113], v[150:153], v[196:199], v[110:113]
	v_mfma_f32_16x16x32_bf16 v[102:105], v[158:161], v[196:199], v[102:105]
	v_mfma_f32_16x16x32_bf16 v[94:97], v[150:153], v[204:207], v[94:97]
	v_mfma_f32_16x16x32_bf16 v[86:89], v[158:161], v[204:207], v[86:89]
	v_mfma_f32_16x16x32_bf16 v[78:81], v[150:153], v[212:215], v[78:81]
	v_mfma_f32_16x16x32_bf16 v[70:73], v[158:161], v[212:215], v[70:73]
	v_mfma_f32_16x16x32_bf16 v[126:129], v[154:157], v[192:195], v[126:129]
	v_mfma_f32_16x16x32_bf16 v[118:121], v[162:165], v[192:195], v[118:121]
	v_mfma_f32_16x16x32_bf16 v[110:113], v[154:157], v[200:203], v[110:113]
	v_mfma_f32_16x16x32_bf16 v[102:105], v[162:165], v[200:203], v[102:105]
	v_mfma_f32_16x16x32_bf16 v[94:97], v[154:157], v[208:211], v[94:97]
	v_mfma_f32_16x16x32_bf16 v[86:89], v[162:165], v[208:211], v[86:89]
	v_mfma_f32_16x16x32_bf16 v[78:81], v[154:157], v[216:219], v[78:81]
	v_mfma_f32_16x16x32_bf16 v[70:73], v[162:165], v[216:219], v[70:73]
	s_setprio 0
	s_setprio 1
	v_mfma_f32_16x16x32_bf16 v[122:125], v[166:169], v[182:185], v[122:125]
	v_mfma_f32_16x16x32_bf16 v[114:117], v[174:177], v[182:185], v[114:117]
	v_mfma_f32_16x16x32_bf16 v[106:109], v[166:169], v[196:199], v[106:109]
	v_mfma_f32_16x16x32_bf16 v[98:101], v[174:177], v[196:199], v[98:101]
	v_mfma_f32_16x16x32_bf16 v[90:93], v[166:169], v[204:207], v[90:93]
	v_mfma_f32_16x16x32_bf16 v[82:85], v[174:177], v[204:207], v[82:85]
	v_mfma_f32_16x16x32_bf16 v[74:77], v[166:169], v[212:215], v[74:77]
	v_mfma_f32_16x16x32_bf16 v[66:69], v[174:177], v[212:215], v[66:69]
	v_mfma_f32_16x16x32_bf16 v[122:125], v[170:173], v[192:195], v[122:125]
	v_mfma_f32_16x16x32_bf16 v[114:117], v[178:181], v[192:195], v[114:117]
	v_mfma_f32_16x16x32_bf16 v[106:109], v[170:173], v[200:203], v[106:109]
	v_mfma_f32_16x16x32_bf16 v[98:101], v[178:181], v[200:203], v[98:101]
	v_mfma_f32_16x16x32_bf16 v[90:93], v[170:173], v[208:211], v[90:93]
	v_mfma_f32_16x16x32_bf16 v[82:85], v[178:181], v[208:211], v[82:85]
	v_mfma_f32_16x16x32_bf16 v[74:77], v[170:173], v[216:219], v[74:77]
	v_mfma_f32_16x16x32_bf16 v[66:69], v[178:181], v[216:219], v[66:69]
	s_setprio 0
	s_barrier
	s_add_i32 s73, s73, s40
	v_lshl_add_u64 v[144:145], s[26:27], 0, v[132:133]
	s_mov_b32 m0, s73
	s_nop 0
	global_load_lds_dwordx4 v[144:145], off
	s_add_i32 m0, s73, 0x2000
	s_add_u32 s74, s26, 0x40000
	v_lshl_add_u64 v[186:187], s[26:27], 0, v[136:137]
	s_addc_u32 s75, s27, 0
	s_add_i32 s73, s76, s40
	global_load_lds_dwordx4 v[186:187], off
	v_lshl_add_u64 v[220:221], s[74:75], 0, v[132:133]
	s_mov_b32 m0, s73
	v_lshl_add_u64 v[236:237], s[96:97], 0, v[134:135]
	global_load_lds_dwordx4 v[220:221], off
	v_lshl_add_u64 v[220:221], s[74:75], 0, v[136:137]
	s_add_i32 m0, s73, 0x2000
	s_nop 0
	global_load_lds_dwordx4 v[220:221], off
	v_lshl_add_u64 v[220:221], s[96:97], 0, v[130:131]
	s_mov_b32 m0, s31
	s_nop 0
	global_load_lds_dwordx4 v[220:221], off
	s_mov_b32 m0, s41
	s_nop 0
	global_load_lds_dwordx4 v[236:237], off
	ds_read_b128 v[182:185], v148 offset:16384
	ds_read_b128 v[192:195], v148 offset:17408
	ds_read_b128 v[196:199], v148 offset:18432
	ds_read_b128 v[200:203], v148 offset:19456
	ds_read_b128 v[204:207], v148 offset:20480
	ds_read_b128 v[208:211], v148 offset:21504
	ds_read_b128 v[212:215], v148 offset:22528
	ds_read_b128 v[216:219], v148 offset:23552
	s_waitcnt vmcnt(8)
	s_waitcnt lgkmcnt(0)
	s_barrier
	s_setprio 1
	s_waitcnt lgkmcnt(0)
	v_mfma_f32_16x16x32_bf16 v[62:65], v[150:153], v[182:185], v[62:65]
	v_mfma_f32_16x16x32_bf16 v[54:57], v[158:161], v[182:185], v[54:57]
	v_mfma_f32_16x16x32_bf16 v[46:49], v[150:153], v[196:199], v[46:49]
	v_mfma_f32_16x16x32_bf16 v[38:41], v[158:161], v[196:199], v[38:41]
	v_mfma_f32_16x16x32_bf16 v[30:33], v[150:153], v[204:207], v[30:33]
	v_mfma_f32_16x16x32_bf16 v[22:25], v[158:161], v[204:207], v[22:25]
	v_mfma_f32_16x16x32_bf16 v[14:17], v[150:153], v[212:215], v[14:17]
	v_mfma_f32_16x16x32_bf16 v[6:9], v[158:161], v[212:215], v[6:9]
	v_mfma_f32_16x16x32_bf16 v[62:65], v[154:157], v[192:195], v[62:65]
	v_mfma_f32_16x16x32_bf16 v[54:57], v[162:165], v[192:195], v[54:57]
	v_mfma_f32_16x16x32_bf16 v[46:49], v[154:157], v[200:203], v[46:49]
	v_mfma_f32_16x16x32_bf16 v[38:41], v[162:165], v[200:203], v[38:41]
	v_mfma_f32_16x16x32_bf16 v[30:33], v[154:157], v[208:211], v[30:33]
	v_mfma_f32_16x16x32_bf16 v[22:25], v[162:165], v[208:211], v[22:25]
	v_mfma_f32_16x16x32_bf16 v[14:17], v[154:157], v[216:219], v[14:17]
	v_mfma_f32_16x16x32_bf16 v[6:9], v[162:165], v[216:219], v[6:9]
	s_setprio 0
	s_setprio 1
	v_mfma_f32_16x16x32_bf16 v[58:61], v[166:169], v[182:185], v[58:61]
	v_mfma_f32_16x16x32_bf16 v[50:53], v[174:177], v[182:185], v[50:53]
	v_mfma_f32_16x16x32_bf16 v[42:45], v[166:169], v[196:199], v[42:45]
	v_mfma_f32_16x16x32_bf16 v[34:37], v[174:177], v[196:199], v[34:37]
	v_mfma_f32_16x16x32_bf16 v[26:29], v[166:169], v[204:207], v[26:29]
	v_mfma_f32_16x16x32_bf16 v[18:21], v[174:177], v[204:207], v[18:21]
	v_mfma_f32_16x16x32_bf16 v[10:13], v[166:169], v[212:215], v[10:13]
	v_mfma_f32_16x16x32_bf16 v[2:5], v[174:177], v[212:215], v[2:5]
	v_mfma_f32_16x16x32_bf16 v[58:61], v[170:173], v[192:195], v[58:61]
	v_mfma_f32_16x16x32_bf16 v[50:53], v[178:181], v[192:195], v[50:53]
	v_mfma_f32_16x16x32_bf16 v[42:45], v[170:173], v[200:203], v[42:45]
	v_mfma_f32_16x16x32_bf16 v[34:37], v[178:181], v[200:203], v[34:37]
	v_mfma_f32_16x16x32_bf16 v[26:29], v[170:173], v[208:211], v[26:29]
	v_mfma_f32_16x16x32_bf16 v[18:21], v[178:181], v[208:211], v[18:21]
	v_mfma_f32_16x16x32_bf16 v[10:13], v[170:173], v[216:219], v[10:13]
	v_mfma_f32_16x16x32_bf16 v[2:5], v[178:181], v[216:219], v[2:5]
	s_setprio 0
	s_barrier
	s_add_i32 s73, 0, 0x18000
	s_add_i32 s76, 0, 0x1c000
	s_add_u32 s74, s96, 0x40000
	s_addc_u32 s75, s97, 0
	s_mov_b32 m0, s42
	v_lshl_add_u64 v[238:239], s[74:75], 0, v[130:131]
	global_load_lds_dwordx4 v[238:239], off
	v_lshl_add_u64 v[238:239], s[74:75], 0, v[134:135]
	s_mov_b32 m0, s43
	s_nop 0
	global_load_lds_dwordx4 v[238:239], off
	v_add_u32_e32 v149, s73, v146
	ds_read_b128 v[150:153], v149
	ds_read_b128 v[154:157], v149 offset:1024
	ds_read_b128 v[158:161], v149 offset:2048
	ds_read_b128 v[162:165], v149 offset:3072
	v_add_u32_e32 v149, s76, v146
	ds_read_b128 v[166:169], v149
	ds_read_b128 v[170:173], v149 offset:1024
	ds_read_b128 v[174:177], v149 offset:2048
	ds_read_b128 v[178:181], v149 offset:3072
	ds_read_b128 v[182:185], v148 offset:32768
	ds_read_b128 v[192:195], v148 offset:33792
	ds_read_b128 v[196:199], v148 offset:34816
	ds_read_b128 v[200:203], v148 offset:35840
	ds_read_b128 v[204:207], v148 offset:36864
	ds_read_b128 v[208:211], v148 offset:37888
	ds_read_b128 v[212:215], v148 offset:38912
	ds_read_b128 v[216:219], v148 offset:39936
	s_waitcnt vmcnt(8)
	s_waitcnt lgkmcnt(0)
	s_barrier
	s_setprio 1
	s_waitcnt lgkmcnt(0)
	v_mfma_f32_16x16x32_bf16 v[126:129], v[150:153], v[182:185], v[126:129]
	v_mfma_f32_16x16x32_bf16 v[118:121], v[158:161], v[182:185], v[118:121]
	v_mfma_f32_16x16x32_bf16 v[110:113], v[150:153], v[196:199], v[110:113]
	v_mfma_f32_16x16x32_bf16 v[102:105], v[158:161], v[196:199], v[102:105]
	v_mfma_f32_16x16x32_bf16 v[94:97], v[150:153], v[204:207], v[94:97]
	v_mfma_f32_16x16x32_bf16 v[86:89], v[158:161], v[204:207], v[86:89]
	v_mfma_f32_16x16x32_bf16 v[78:81], v[150:153], v[212:215], v[78:81]
	v_mfma_f32_16x16x32_bf16 v[70:73], v[158:161], v[212:215], v[70:73]
	v_mfma_f32_16x16x32_bf16 v[126:129], v[154:157], v[192:195], v[126:129]
	v_mfma_f32_16x16x32_bf16 v[118:121], v[162:165], v[192:195], v[118:121]
	v_mfma_f32_16x16x32_bf16 v[110:113], v[154:157], v[200:203], v[110:113]
	v_mfma_f32_16x16x32_bf16 v[102:105], v[162:165], v[200:203], v[102:105]
	v_mfma_f32_16x16x32_bf16 v[94:97], v[154:157], v[208:211], v[94:97]
	v_mfma_f32_16x16x32_bf16 v[86:89], v[162:165], v[208:211], v[86:89]
	v_mfma_f32_16x16x32_bf16 v[78:81], v[154:157], v[216:219], v[78:81]
	v_mfma_f32_16x16x32_bf16 v[70:73], v[162:165], v[216:219], v[70:73]
	s_setprio 0
	s_setprio 1
	v_mfma_f32_16x16x32_bf16 v[122:125], v[166:169], v[182:185], v[122:125]
	v_mfma_f32_16x16x32_bf16 v[114:117], v[174:177], v[182:185], v[114:117]
	v_mfma_f32_16x16x32_bf16 v[106:109], v[166:169], v[196:199], v[106:109]
	v_mfma_f32_16x16x32_bf16 v[98:101], v[174:177], v[196:199], v[98:101]
	v_mfma_f32_16x16x32_bf16 v[90:93], v[166:169], v[204:207], v[90:93]
	v_mfma_f32_16x16x32_bf16 v[82:85], v[174:177], v[204:207], v[82:85]
	v_mfma_f32_16x16x32_bf16 v[74:77], v[166:169], v[212:215], v[74:77]
	v_mfma_f32_16x16x32_bf16 v[66:69], v[174:177], v[212:215], v[66:69]
	v_mfma_f32_16x16x32_bf16 v[122:125], v[170:173], v[192:195], v[122:125]
	v_mfma_f32_16x16x32_bf16 v[114:117], v[178:181], v[192:195], v[114:117]
	v_mfma_f32_16x16x32_bf16 v[106:109], v[170:173], v[200:203], v[106:109]
	v_mfma_f32_16x16x32_bf16 v[98:101], v[178:181], v[200:203], v[98:101]
	v_mfma_f32_16x16x32_bf16 v[90:93], v[170:173], v[208:211], v[90:93]
	v_mfma_f32_16x16x32_bf16 v[82:85], v[178:181], v[208:211], v[82:85]
	v_mfma_f32_16x16x32_bf16 v[74:77], v[170:173], v[216:219], v[74:77]
	v_mfma_f32_16x16x32_bf16 v[66:69], v[178:181], v[216:219], v[66:69]
	s_setprio 0
	s_barrier
	s_add_i32 s73, s73, s40
	v_lshl_add_u64 v[144:145], v[144:145], 0, s[94:95]
	s_mov_b32 m0, s73
	s_nop 0
	global_load_lds_dwordx4 v[144:145], off
	s_add_i32 m0, s73, 0x2000
	s_add_u32 s26, s26, 0x40080
	v_lshl_add_u64 v[144:145], v[186:187], 0, s[94:95]
	s_addc_u32 s27, s27, 0
	s_add_i32 s73, s76, s40
	global_load_lds_dwordx4 v[144:145], off
	v_lshl_add_u64 v[144:145], s[26:27], 0, v[132:133]
	s_mov_b32 m0, s73
	s_nop 0
	global_load_lds_dwordx4 v[144:145], off
	v_lshl_add_u64 v[144:145], s[26:27], 0, v[136:137]
	s_add_i32 m0, s73, 0x2000
	s_nop 0
	global_load_lds_dwordx4 v[144:145], off
	v_lshl_add_u64 v[144:145], v[220:221], 0, s[94:95]
	s_mov_b32 m0, s45
	s_nop 0
	global_load_lds_dwordx4 v[144:145], off
	v_lshl_add_u64 v[144:145], v[236:237], 0, s[94:95]
	s_mov_b32 m0, s50
	s_nop 0
	global_load_lds_dwordx4 v[144:145], off
	ds_read_b128 v[182:185], v148 offset:49152
	ds_read_b128 v[192:195], v148 offset:50176
	ds_read_b128 v[196:199], v148 offset:51200
	ds_read_b128 v[200:203], v148 offset:52224
	ds_read_b128 v[204:207], v148 offset:53248
	ds_read_b128 v[208:211], v148 offset:54272
	ds_read_b128 v[212:215], v148 offset:55296
	ds_read_b128 v[216:219], v148 offset:56320
	s_waitcnt vmcnt(8)
	s_waitcnt lgkmcnt(0)
	s_barrier
	s_setprio 1
	s_waitcnt lgkmcnt(0)
	v_mfma_f32_16x16x32_bf16 v[62:65], v[150:153], v[182:185], v[62:65]
	v_mfma_f32_16x16x32_bf16 v[54:57], v[158:161], v[182:185], v[54:57]
	v_mfma_f32_16x16x32_bf16 v[46:49], v[150:153], v[196:199], v[46:49]
	v_mfma_f32_16x16x32_bf16 v[38:41], v[158:161], v[196:199], v[38:41]
	v_mfma_f32_16x16x32_bf16 v[30:33], v[150:153], v[204:207], v[30:33]
	v_mfma_f32_16x16x32_bf16 v[22:25], v[158:161], v[204:207], v[22:25]
	v_mfma_f32_16x16x32_bf16 v[14:17], v[150:153], v[212:215], v[14:17]
	v_mfma_f32_16x16x32_bf16 v[6:9], v[158:161], v[212:215], v[6:9]
	v_mfma_f32_16x16x32_bf16 v[62:65], v[154:157], v[192:195], v[62:65]
	v_mfma_f32_16x16x32_bf16 v[54:57], v[162:165], v[192:195], v[54:57]
	v_mfma_f32_16x16x32_bf16 v[46:49], v[154:157], v[200:203], v[46:49]
	v_mfma_f32_16x16x32_bf16 v[38:41], v[162:165], v[200:203], v[38:41]
	v_mfma_f32_16x16x32_bf16 v[30:33], v[154:157], v[208:211], v[30:33]
	v_mfma_f32_16x16x32_bf16 v[22:25], v[162:165], v[208:211], v[22:25]
	v_mfma_f32_16x16x32_bf16 v[14:17], v[154:157], v[216:219], v[14:17]
	v_mfma_f32_16x16x32_bf16 v[6:9], v[162:165], v[216:219], v[6:9]
	s_setprio 0
	s_setprio 1
	v_mfma_f32_16x16x32_bf16 v[58:61], v[166:169], v[182:185], v[58:61]
	v_mfma_f32_16x16x32_bf16 v[50:53], v[174:177], v[182:185], v[50:53]
	v_mfma_f32_16x16x32_bf16 v[42:45], v[166:169], v[196:199], v[42:45]
	v_mfma_f32_16x16x32_bf16 v[34:37], v[174:177], v[196:199], v[34:37]
	v_mfma_f32_16x16x32_bf16 v[26:29], v[166:169], v[204:207], v[26:29]
	v_mfma_f32_16x16x32_bf16 v[18:21], v[174:177], v[204:207], v[18:21]
	v_mfma_f32_16x16x32_bf16 v[10:13], v[166:169], v[212:215], v[10:13]
	v_mfma_f32_16x16x32_bf16 v[2:5], v[174:177], v[212:215], v[2:5]
	v_mfma_f32_16x16x32_bf16 v[58:61], v[170:173], v[192:195], v[58:61]
	v_mfma_f32_16x16x32_bf16 v[50:53], v[178:181], v[192:195], v[50:53]
	v_mfma_f32_16x16x32_bf16 v[42:45], v[170:173], v[200:203], v[42:45]
	v_mfma_f32_16x16x32_bf16 v[34:37], v[178:181], v[200:203], v[34:37]
	v_mfma_f32_16x16x32_bf16 v[26:29], v[170:173], v[208:211], v[26:29]
	v_mfma_f32_16x16x32_bf16 v[18:21], v[178:181], v[208:211], v[18:21]
	v_mfma_f32_16x16x32_bf16 v[10:13], v[170:173], v[216:219], v[10:13]
	v_mfma_f32_16x16x32_bf16 v[2:5], v[178:181], v[216:219], v[2:5]
	s_setprio 0
	s_barrier
	s_add_i32 s72, s72, 2
	s_add_u32 s34, s34, 0x100
	s_addc_u32 s35, s35, 0
	s_add_u32 s63, s63, 0x100
	s_addc_u32 s65, s65, 0
	s_cmp_gt_u32 s72, 13
	s_cbranch_scc0 .LBB0_169
	s_and_b64 vcc, exec, s[8:9]
	s_cbranch_vccz .LBB0_172
	s_barrier
